# barrier: XCD leaders broadcast completion into per-XCD DONE words (no TOP atomic round trip, no second hop)
# speedup vs baseline: 1.0046x; 1.0046x over previous
.LBB0_163:
	s_or_b64 exec, exec, s[2:3]
	s_cmp_eq_u32 s71, 2
	s_cbranch_scc1 .LBB0_226
	s_cmp_lg_u32 s70, 1
	s_mov_b64 s[2:3], -1
	s_cbranch_scc0 .LBB0_214
	s_waitcnt vmcnt(0)
	s_barrier
	s_mov_b64 s[2:3], exec
	v_readlane_b32 s4, v253, 6
	v_readlane_b32 s5, v253, 7
	s_and_b64 s[4:5], s[2:3], s[4:5]
	s_mov_b64 exec, s[4:5]
	s_cbranch_execz .LBB0_213
	v_readlane_b32 s98, v253, 2
	v_readlane_b32 s99, v253, 3
	v_mov_b32_e32 v1, 0x12000
	s_waitcnt vmcnt(0) expcnt(0) lgkmcnt(0)
	s_load_dwordx2 s[98:99], s[98:99], 0xf8
	ds_read_b128 v[4:7], v1
	s_getreg_b32 s100, hwreg(HW_REG_XCC_ID, 0, 4)
	s_and_b32 s100, s100, 15
	s_lshl_b32 s100, s100, 8
	s_add_u32 s100, s100, 0x38e00000
	s_waitcnt lgkmcnt(0)
	s_add_u32 s100, s98, s100
	s_addc_u32 s101, s99, 0
	v_mov_b32_e32 v2, 1
	v_mov_b32_e32 v3, 0x1400
	global_atomic_add v8, v3, v2, s[100:101] sc0
	v_cvt_f32_u32_e32 v12, v4
	v_rcp_iflag_f32_e32 v12, v12
	v_sub_u32_e32 v13, 0, v4
	s_nop 1
	v_mul_f32_e32 v12, 0x4f7ffffe, v12
	v_cvt_u32_f32_e32 v12, v12
	v_mul_lo_u32 v13, v13, v12
	v_mul_hi_u32 v13, v12, v13
	v_add_u32_e32 v12, v12, v13
	s_waitcnt vmcnt(0)
	buffer_inv sc1
	v_mul_hi_u32 v12, v8, v12
	v_mul_lo_u32 v13, v12, v4
	v_sub_u32_e32 v14, v8, v13
	v_add_u32_e32 v15, 1, v12
	v_cmp_ge_u32_e32 vcc, v14, v4
	v_sub_u32_e32 v13, v14, v4
	s_nop 1
	v_cndmask_b32_e32 v12, v12, v15, vcc
	v_cndmask_b32_e32 v14, v14, v13, vcc
	v_add_u32_e32 v15, 1, v12
	v_cmp_ge_u32_e32 vcc, v14, v4
	s_nop 1
	v_cndmask_b32_e32 v6, v12, v15, vcc
	v_add_u32_e32 v9, 1, v6
	v_mul_lo_u32 v10, v9, v4
	v_mul_lo_u32 v11, v6, v5
	v_add_u32_e32 v8, 1, v8
	v_cmp_ne_u32_e32 vcc, v8, v10
	s_cbranch_vccnz .Lxb_spin_1
	v_mov_b32_e32 v3, 0x1480
	v_add_u32_e32 v14, -1, v4
	v_mul_lo_u32 v14, v14, v6
	buffer_wbl2 sc1
	v_mov_b32_e32 v16, 0

.Lxb_iok_1:
	v_mov_b32_e32 v12, 0x38e02480
	global_atomic_add v12, v2, s[98:99]
	v_mov_b32_e32 v13, 0x38e02580
	global_atomic_add v13, v2, s[98:99]
	v_mov_b32_e32 v14, 0x38e02680
	global_atomic_add v14, v2, s[98:99]
	v_mov_b32_e32 v15, 0x38e02780
	global_atomic_add v15, v2, s[98:99]
	v_mov_b32_e32 v12, 0x38e02880
	global_atomic_add v12, v2, s[98:99]
	v_mov_b32_e32 v13, 0x38e02980
	global_atomic_add v13, v2, s[98:99]
	v_mov_b32_e32 v14, 0x38e02a80
	global_atomic_add v14, v2, s[98:99]
	v_mov_b32_e32 v15, 0x38e02b80
	global_atomic_add v15, v2, s[98:99]
	v_mov_b32_e32 v12, 0x38e02c80
	global_atomic_add v12, v2, s[98:99]
	v_mov_b32_e32 v13, 0x38e02d80
	global_atomic_add v13, v2, s[98:99]
	v_mov_b32_e32 v14, 0x38e02e80
	global_atomic_add v14, v2, s[98:99]
	v_mov_b32_e32 v15, 0x38e02f80
	global_atomic_add v15, v2, s[98:99]
	v_mov_b32_e32 v12, 0x38e03080
	global_atomic_add v12, v2, s[98:99]
	v_mov_b32_e32 v13, 0x38e03180
	global_atomic_add v13, v2, s[98:99]
	v_mov_b32_e32 v14, 0x38e03280
	global_atomic_add v14, v2, s[98:99]
	v_mov_b32_e32 v15, 0x38e03380
	global_atomic_add v15, v2, s[98:99]
	s_branch .Lxb_spinl_1

.Lxb_spinl_1:
	v_mov_b32_e32 v3, 0x2480
	v_mov_b32_e32 v16, 0
.Lxb_poll_1:
	global_load_dword v8, v3, s[100:101] sc1
	s_waitcnt vmcnt(0)
	v_cmp_ge_u32_e32 vcc, v8, v11
	s_cbranch_vccnz .Lxb_done_1
	s_sleep 1
	v_add_u32_e32 v16, 1, v16
	v_cmp_gt_u32_e32 vcc, 0x40000, v16
	s_cbranch_vccnz .Lxb_poll_1

.LBB0_271:
	s_add_i32 s2, s30, 1
	s_cmp_ge_i32 s2, s71
	s_cbranch_scc1 .LBB0_284
	s_cmp_lg_u32 s30, s70
	s_mov_b64 s[44:45], -1
	s_cbranch_scc0 .LBB0_323
	s_waitcnt vmcnt(0)
	s_barrier
	s_mov_b64 s[44:45], exec
	v_readlane_b32 s38, v253, 6
	v_readlane_b32 s39, v253, 7
	s_and_b64 s[38:39], s[44:45], s[38:39]
	s_mov_b64 exec, s[38:39]
	s_cbranch_execz .LBB0_322
	v_readlane_b32 s98, v253, 2
	v_readlane_b32 s99, v253, 3
	v_mov_b32_e32 v1, 0x12000
	s_waitcnt vmcnt(0) expcnt(0) lgkmcnt(0)
	s_load_dwordx2 s[98:99], s[98:99], 0xf8
	ds_read_b128 v[4:7], v1
	s_getreg_b32 s100, hwreg(HW_REG_XCC_ID, 0, 4)
	s_and_b32 s100, s100, 15
	s_lshl_b32 s100, s100, 8
	s_add_u32 s100, s100, 0x38e00000
	s_waitcnt lgkmcnt(0)
	s_add_u32 s100, s98, s100
	s_addc_u32 s101, s99, 0
	v_mov_b32_e32 v2, 1
	v_mov_b32_e32 v3, 0x1400
	global_atomic_add v8, v3, v2, s[100:101] sc0
	v_cvt_f32_u32_e32 v12, v4
	v_rcp_iflag_f32_e32 v12, v12
	v_sub_u32_e32 v13, 0, v4
	s_nop 1
	v_mul_f32_e32 v12, 0x4f7ffffe, v12
	v_cvt_u32_f32_e32 v12, v12
	v_mul_lo_u32 v13, v13, v12
	v_mul_hi_u32 v13, v12, v13
	v_add_u32_e32 v12, v12, v13
	s_waitcnt vmcnt(0)
	buffer_inv sc1
	v_mul_hi_u32 v12, v8, v12
	v_mul_lo_u32 v13, v12, v4
	v_sub_u32_e32 v14, v8, v13
	v_add_u32_e32 v15, 1, v12
	v_cmp_ge_u32_e32 vcc, v14, v4
	v_sub_u32_e32 v13, v14, v4
	s_nop 1
	v_cndmask_b32_e32 v12, v12, v15, vcc
	v_cndmask_b32_e32 v14, v14, v13, vcc
	v_add_u32_e32 v15, 1, v12
	v_cmp_ge_u32_e32 vcc, v14, v4
	s_nop 1
	v_cndmask_b32_e32 v6, v12, v15, vcc
	v_add_u32_e32 v9, 1, v6
	v_mul_lo_u32 v10, v9, v4
	v_mul_lo_u32 v11, v6, v5
	v_add_u32_e32 v8, 1, v8
	v_cmp_ne_u32_e32 vcc, v8, v10
	s_cbranch_vccnz .Lxb_spin_2
	v_mov_b32_e32 v3, 0x1480
	v_add_u32_e32 v14, -1, v4
	v_mul_lo_u32 v14, v14, v6
	buffer_wbl2 sc1
	v_mov_b32_e32 v16, 0

.LBB0_384:
	s_add_i32 s31, s30, 2
	s_cmp_ge_i32 s31, s71
	s_cbranch_scc1 .LBB0_447
	s_cmp_lg_u32 s2, s70
	s_mov_b64 s[44:45], -1
	s_cbranch_scc0 .LBB0_435
	s_waitcnt vmcnt(0)
	s_barrier
	s_mov_b64 s[44:45], exec
	v_readlane_b32 s2, v253, 6
	v_readlane_b32 s3, v253, 7
	s_and_b64 s[2:3], s[44:45], s[2:3]
	s_mov_b64 exec, s[2:3]
	s_cbranch_execz .LBB0_434
	v_readlane_b32 s98, v253, 2
	v_readlane_b32 s99, v253, 3
	v_mov_b32_e32 v1, 0x12000
	s_waitcnt vmcnt(0) expcnt(0) lgkmcnt(0)
	s_load_dwordx2 s[98:99], s[98:99], 0xf8
	ds_read_b128 v[4:7], v1
	s_getreg_b32 s100, hwreg(HW_REG_XCC_ID, 0, 4)
	s_and_b32 s100, s100, 15
	s_lshl_b32 s100, s100, 8
	s_add_u32 s100, s100, 0x38e00000
	s_waitcnt lgkmcnt(0)
	s_add_u32 s100, s98, s100
	s_addc_u32 s101, s99, 0
	v_mov_b32_e32 v2, 1
	v_mov_b32_e32 v3, 0x1400
	global_atomic_add v8, v3, v2, s[100:101] sc0
	v_cvt_f32_u32_e32 v12, v4
	v_rcp_iflag_f32_e32 v12, v12
	v_sub_u32_e32 v13, 0, v4
	s_nop 1
	v_mul_f32_e32 v12, 0x4f7ffffe, v12
	v_cvt_u32_f32_e32 v12, v12
	v_mul_lo_u32 v13, v13, v12
	v_mul_hi_u32 v13, v12, v13
	v_add_u32_e32 v12, v12, v13
	s_waitcnt vmcnt(0)
	buffer_inv sc1
	v_mul_hi_u32 v12, v8, v12
	v_mul_lo_u32 v13, v12, v4
	v_sub_u32_e32 v14, v8, v13
	v_add_u32_e32 v15, 1, v12
	v_cmp_ge_u32_e32 vcc, v14, v4
	v_sub_u32_e32 v13, v14, v4
	s_nop 1
	v_cndmask_b32_e32 v12, v12, v15, vcc
	v_cndmask_b32_e32 v14, v14, v13, vcc
	v_add_u32_e32 v15, 1, v12
	v_cmp_ge_u32_e32 vcc, v14, v4
	s_nop 1
	v_cndmask_b32_e32 v6, v12, v15, vcc
	v_add_u32_e32 v9, 1, v6
	v_mul_lo_u32 v10, v9, v4
	v_mul_lo_u32 v11, v6, v5
	v_add_u32_e32 v8, 1, v8
	v_cmp_ne_u32_e32 vcc, v8, v10
	s_cbranch_vccnz .Lxb_spin_3
	v_mov_b32_e32 v3, 0x1480
	v_add_u32_e32 v14, -1, v4
	v_mul_lo_u32 v14, v14, v6
	buffer_wbl2 sc1
	v_mov_b32_e32 v16, 0

.LBB0_459:
	s_add_i32 s31, s30, 1
	s_cmp_ge_i32 s31, s71
	s_cbranch_scc1 .LBB0_522
	s_cmp_lg_u32 s30, s70
	s_mov_b64 s[42:43], -1
	s_cbranch_scc0 .LBB0_510
	s_waitcnt vmcnt(0)
	s_barrier
	s_mov_b64 s[42:43], exec
	v_readlane_b32 s2, v253, 6
	v_readlane_b32 s3, v253, 7
	s_and_b64 s[2:3], s[42:43], s[2:3]
	s_mov_b64 exec, s[2:3]
	s_cbranch_execz .LBB0_509
	v_readlane_b32 s98, v253, 2
	v_readlane_b32 s99, v253, 3
	v_mov_b32_e32 v1, 0x12000
	s_waitcnt vmcnt(0) expcnt(0) lgkmcnt(0)
	s_load_dwordx2 s[98:99], s[98:99], 0xf8
	ds_read_b128 v[4:7], v1
	s_getreg_b32 s100, hwreg(HW_REG_XCC_ID, 0, 4)
	s_and_b32 s100, s100, 15
	s_lshl_b32 s100, s100, 8
	s_add_u32 s100, s100, 0x38e00000
	s_waitcnt lgkmcnt(0)
	s_add_u32 s100, s98, s100
	s_addc_u32 s101, s99, 0
	v_mov_b32_e32 v2, 1
	v_mov_b32_e32 v3, 0x1400
	global_atomic_add v8, v3, v2, s[100:101] sc0
	v_cvt_f32_u32_e32 v12, v4
	v_rcp_iflag_f32_e32 v12, v12
	v_sub_u32_e32 v13, 0, v4
	s_nop 1
	v_mul_f32_e32 v12, 0x4f7ffffe, v12
	v_cvt_u32_f32_e32 v12, v12
	v_mul_lo_u32 v13, v13, v12
	v_mul_hi_u32 v13, v12, v13
	v_add_u32_e32 v12, v12, v13
	s_waitcnt vmcnt(0)
	buffer_inv sc1
	v_mul_hi_u32 v12, v8, v12
	v_mul_lo_u32 v13, v12, v4
	v_sub_u32_e32 v14, v8, v13
	v_add_u32_e32 v15, 1, v12
	v_cmp_ge_u32_e32 vcc, v14, v4
	v_sub_u32_e32 v13, v14, v4
	s_nop 1
	v_cndmask_b32_e32 v12, v12, v15, vcc
	v_cndmask_b32_e32 v14, v14, v13, vcc
	v_add_u32_e32 v15, 1, v12
	v_cmp_ge_u32_e32 vcc, v14, v4
	s_nop 1
	v_cndmask_b32_e32 v6, v12, v15, vcc
	v_add_u32_e32 v9, 1, v6
	v_mul_lo_u32 v10, v9, v4
	v_mul_lo_u32 v11, v6, v5
	v_add_u32_e32 v8, 1, v8
	v_cmp_ne_u32_e32 vcc, v8, v10
	s_cbranch_vccnz .Lxb_spin_4
	v_mov_b32_e32 v3, 0x1480
	v_add_u32_e32 v14, -1, v4
	v_mul_lo_u32 v14, v14, v6
	buffer_wbl2 sc1
	v_mov_b32_e32 v16, 0

.LBB0_641:
	s_add_i32 s3, s30, 2
	s_cmp_ge_i32 s3, s71
	s_cbranch_scc1 .LBB0_704
	s_cmp_lg_u32 s31, s70
	s_mov_b64 s[42:43], -1
	s_cbranch_scc0 .LBB0_692
	s_waitcnt vmcnt(0)
	s_waitcnt lgkmcnt(0)
	s_barrier
	s_mov_b64 s[42:43], exec
	v_readlane_b32 s38, v253, 6
	v_readlane_b32 s39, v253, 7
	s_and_b64 s[38:39], s[42:43], s[38:39]
	s_mov_b64 exec, s[38:39]
	s_cbranch_execz .LBB0_691
	v_readlane_b32 s98, v253, 2
	v_readlane_b32 s99, v253, 3
	v_mov_b32_e32 v1, 0x12000
	s_waitcnt vmcnt(0) expcnt(0) lgkmcnt(0)
	s_load_dwordx2 s[98:99], s[98:99], 0xf8
	ds_read_b128 v[4:7], v1
	s_getreg_b32 s100, hwreg(HW_REG_XCC_ID, 0, 4)
	s_and_b32 s100, s100, 15
	s_lshl_b32 s100, s100, 8
	s_add_u32 s100, s100, 0x38e00000
	s_waitcnt lgkmcnt(0)
	s_add_u32 s100, s98, s100
	s_addc_u32 s101, s99, 0
	v_mov_b32_e32 v2, 1
	v_mov_b32_e32 v3, 0x1400
	global_atomic_add v8, v3, v2, s[100:101] sc0
	v_cvt_f32_u32_e32 v12, v4
	v_rcp_iflag_f32_e32 v12, v12
	v_sub_u32_e32 v13, 0, v4
	s_nop 1
	v_mul_f32_e32 v12, 0x4f7ffffe, v12
	v_cvt_u32_f32_e32 v12, v12
	v_mul_lo_u32 v13, v13, v12
	v_mul_hi_u32 v13, v12, v13
	v_add_u32_e32 v12, v12, v13
	s_waitcnt vmcnt(0)
	buffer_inv sc1
	v_mul_hi_u32 v12, v8, v12
	v_mul_lo_u32 v13, v12, v4
	v_sub_u32_e32 v14, v8, v13
	v_add_u32_e32 v15, 1, v12
	v_cmp_ge_u32_e32 vcc, v14, v4
	v_sub_u32_e32 v13, v14, v4
	s_nop 1
	v_cndmask_b32_e32 v12, v12, v15, vcc
	v_cndmask_b32_e32 v14, v14, v13, vcc
	v_add_u32_e32 v15, 1, v12
	v_cmp_ge_u32_e32 vcc, v14, v4
	s_nop 1
	v_cndmask_b32_e32 v6, v12, v15, vcc
	v_add_u32_e32 v9, 1, v6
	v_mul_lo_u32 v10, v9, v4
	v_mul_lo_u32 v11, v6, v5
	v_add_u32_e32 v8, 1, v8
	v_cmp_ne_u32_e32 vcc, v8, v10
	s_cbranch_vccnz .Lxb_spin_5
	v_mov_b32_e32 v3, 0x1480
	v_add_u32_e32 v14, -1, v4
	v_mul_lo_u32 v14, v14, v6
	buffer_wbl2 sc1
	v_mov_b32_e32 v16, 0

.LBB0_714:
	s_or_b64 exec, exec, s[44:45]
	s_add_i32 s2, s30, 3
	s_cmp_ge_i32 s2, s71
	s_cbranch_scc1 .LBB0_777
	s_cmp_lg_u32 s3, s70
	s_mov_b64 s[42:43], -1
	s_cbranch_scc0 .LBB0_765
	s_waitcnt vmcnt(0)
	s_waitcnt lgkmcnt(0)
	s_barrier
	s_mov_b64 s[42:43], exec
	v_readlane_b32 s38, v253, 6
	v_readlane_b32 s39, v253, 7
	s_and_b64 s[38:39], s[42:43], s[38:39]
	s_mov_b64 exec, s[38:39]
	s_cbranch_execz .LBB0_764
	v_readlane_b32 s98, v253, 2
	v_readlane_b32 s99, v253, 3
	v_mov_b32_e32 v1, 0x12000
	s_waitcnt vmcnt(0) expcnt(0) lgkmcnt(0)
	s_load_dwordx2 s[98:99], s[98:99], 0xf8
	ds_read_b128 v[4:7], v1
	s_getreg_b32 s100, hwreg(HW_REG_XCC_ID, 0, 4)
	s_and_b32 s100, s100, 15
	s_lshl_b32 s100, s100, 8
	s_add_u32 s100, s100, 0x38e00000
	s_waitcnt lgkmcnt(0)
	s_add_u32 s100, s98, s100
	s_addc_u32 s101, s99, 0
	v_mov_b32_e32 v2, 1
	v_mov_b32_e32 v3, 0x1400
	global_atomic_add v8, v3, v2, s[100:101] sc0
	v_cvt_f32_u32_e32 v12, v4
	v_rcp_iflag_f32_e32 v12, v12
	v_sub_u32_e32 v13, 0, v4
	s_nop 1
	v_mul_f32_e32 v12, 0x4f7ffffe, v12
	v_cvt_u32_f32_e32 v12, v12
	v_mul_lo_u32 v13, v13, v12
	v_mul_hi_u32 v13, v12, v13
	v_add_u32_e32 v12, v12, v13
	s_waitcnt vmcnt(0)
	buffer_inv sc1
	v_mul_hi_u32 v12, v8, v12
	v_mul_lo_u32 v13, v12, v4
	v_sub_u32_e32 v14, v8, v13
	v_add_u32_e32 v15, 1, v12
	v_cmp_ge_u32_e32 vcc, v14, v4
	v_sub_u32_e32 v13, v14, v4
	s_nop 1
	v_cndmask_b32_e32 v12, v12, v15, vcc
	v_cndmask_b32_e32 v14, v14, v13, vcc
	v_add_u32_e32 v15, 1, v12
	v_cmp_ge_u32_e32 vcc, v14, v4
	s_nop 1
	v_cndmask_b32_e32 v6, v12, v15, vcc
	v_add_u32_e32 v9, 1, v6
	v_mul_lo_u32 v10, v9, v4
	v_mul_lo_u32 v11, v6, v5
	v_add_u32_e32 v8, 1, v8
	v_cmp_ne_u32_e32 vcc, v8, v10
	s_cbranch_vccnz .Lxb_spin_6
	v_mov_b32_e32 v3, 0x1480
	v_add_u32_e32 v14, -1, v4
	v_mul_lo_u32 v14, v14, v6
	buffer_wbl2 sc1
	v_mov_b32_e32 v16, 0

.LBB0_789:
	s_add_i32 s31, s30, 4
	s_cmp_ge_i32 s31, s71
	s_cbranch_scc1 .LBB0_852
	s_cmp_lg_u32 s2, s70
	s_mov_b64 s[42:43], -1
	s_cbranch_scc0 .LBB0_840
	s_waitcnt vmcnt(0)
	s_waitcnt lgkmcnt(0)
	s_barrier
	s_mov_b64 s[42:43], exec
	v_readlane_b32 s2, v253, 6
	v_readlane_b32 s3, v253, 7
	s_and_b64 s[2:3], s[42:43], s[2:3]
	s_mov_b64 exec, s[2:3]
	s_cbranch_execz .LBB0_839
	v_readlane_b32 s98, v253, 2
	v_readlane_b32 s99, v253, 3
	v_mov_b32_e32 v1, 0x12000
	s_waitcnt vmcnt(0) expcnt(0) lgkmcnt(0)
	s_load_dwordx2 s[98:99], s[98:99], 0xf8
	ds_read_b128 v[4:7], v1
	s_getreg_b32 s100, hwreg(HW_REG_XCC_ID, 0, 4)
	s_and_b32 s100, s100, 15
	s_lshl_b32 s100, s100, 8
	s_add_u32 s100, s100, 0x38e00000
	s_waitcnt lgkmcnt(0)
	s_add_u32 s100, s98, s100
	s_addc_u32 s101, s99, 0
	v_mov_b32_e32 v2, 1
	v_mov_b32_e32 v3, 0x1400
	global_atomic_add v8, v3, v2, s[100:101] sc0
	v_cvt_f32_u32_e32 v12, v4
	v_rcp_iflag_f32_e32 v12, v12
	v_sub_u32_e32 v13, 0, v4
	s_nop 1
	v_mul_f32_e32 v12, 0x4f7ffffe, v12
	v_cvt_u32_f32_e32 v12, v12
	v_mul_lo_u32 v13, v13, v12
	v_mul_hi_u32 v13, v12, v13
	v_add_u32_e32 v12, v12, v13
	s_waitcnt vmcnt(0)
	buffer_inv sc1
	v_mul_hi_u32 v12, v8, v12
	v_mul_lo_u32 v13, v12, v4
	v_sub_u32_e32 v14, v8, v13
	v_add_u32_e32 v15, 1, v12
	v_cmp_ge_u32_e32 vcc, v14, v4
	v_sub_u32_e32 v13, v14, v4
	s_nop 1
	v_cndmask_b32_e32 v12, v12, v15, vcc
	v_cndmask_b32_e32 v14, v14, v13, vcc
	v_add_u32_e32 v15, 1, v12
	v_cmp_ge_u32_e32 vcc, v14, v4
	s_nop 1
	v_cndmask_b32_e32 v6, v12, v15, vcc
	v_add_u32_e32 v9, 1, v6
	v_mul_lo_u32 v10, v9, v4
	v_mul_lo_u32 v11, v6, v5
	v_add_u32_e32 v8, 1, v8
	v_cmp_ne_u32_e32 vcc, v8, v10
	s_cbranch_vccnz .Lxb_spin_7
	v_mov_b32_e32 v3, 0x1480
	v_add_u32_e32 v14, -1, v4
	v_mul_lo_u32 v14, v14, v6
	buffer_wbl2 sc1
	v_mov_b32_e32 v16, 0

.LBB0_862:
	s_add_i32 s2, s31, 1
	s_cmp_ge_i32 s2, s71
	s_cbranch_scc1 .LBB0_925
	s_cmp_lg_u32 s31, s70
	s_mov_b64 s[44:45], -1
	s_cbranch_scc0 .LBB0_913
	s_waitcnt vmcnt(0)
	s_waitcnt lgkmcnt(0)
	s_barrier
	s_mov_b64 s[44:45], exec
	v_readlane_b32 s38, v253, 6
	v_readlane_b32 s39, v253, 7
	s_and_b64 s[38:39], s[44:45], s[38:39]
	s_mov_b64 exec, s[38:39]
	s_cbranch_execz .LBB0_912
	v_readlane_b32 s98, v253, 2
	v_readlane_b32 s99, v253, 3
	v_mov_b32_e32 v1, 0x12000
	s_waitcnt vmcnt(0) expcnt(0) lgkmcnt(0)
	s_load_dwordx2 s[98:99], s[98:99], 0xf8
	ds_read_b128 v[4:7], v1
	s_getreg_b32 s100, hwreg(HW_REG_XCC_ID, 0, 4)
	s_and_b32 s100, s100, 15
	s_lshl_b32 s100, s100, 8
	s_add_u32 s100, s100, 0x38e00000
	s_waitcnt lgkmcnt(0)
	s_add_u32 s100, s98, s100
	s_addc_u32 s101, s99, 0
	v_mov_b32_e32 v2, 1
	v_mov_b32_e32 v3, 0x1400
	global_atomic_add v8, v3, v2, s[100:101] sc0
	v_cvt_f32_u32_e32 v12, v4
	v_rcp_iflag_f32_e32 v12, v12
	v_sub_u32_e32 v13, 0, v4
	s_nop 1
	v_mul_f32_e32 v12, 0x4f7ffffe, v12
	v_cvt_u32_f32_e32 v12, v12
	v_mul_lo_u32 v13, v13, v12
	v_mul_hi_u32 v13, v12, v13
	v_add_u32_e32 v12, v12, v13
	s_waitcnt vmcnt(0)
	buffer_inv sc1
	v_mul_hi_u32 v12, v8, v12
	v_mul_lo_u32 v13, v12, v4
	v_sub_u32_e32 v14, v8, v13
	v_add_u32_e32 v15, 1, v12
	v_cmp_ge_u32_e32 vcc, v14, v4
	v_sub_u32_e32 v13, v14, v4
	s_nop 1
	v_cndmask_b32_e32 v12, v12, v15, vcc
	v_cndmask_b32_e32 v14, v14, v13, vcc
	v_add_u32_e32 v15, 1, v12
	v_cmp_ge_u32_e32 vcc, v14, v4
	s_nop 1
	v_cndmask_b32_e32 v6, v12, v15, vcc
	v_add_u32_e32 v9, 1, v6
	v_mul_lo_u32 v10, v9, v4
	v_mul_lo_u32 v11, v6, v5
	v_add_u32_e32 v8, 1, v8
	v_cmp_ne_u32_e32 vcc, v8, v10
	s_cbranch_vccnz .Lxb_spin_8
	v_mov_b32_e32 v3, 0x1480
	v_add_u32_e32 v14, -1, v4
	v_mul_lo_u32 v14, v14, v6
	buffer_wbl2 sc1
	v_mov_b32_e32 v16, 0

.LBB0_933:
	s_or_b64 exec, exec, s[46:47]
	s_add_i32 s30, s31, 2
	s_cmp_ge_i32 s30, s71
	s_cbranch_scc1 .LBB0_996
	s_cmp_lg_u32 s2, s70
	s_mov_b64 s[44:45], -1
	s_cbranch_scc0 .LBB0_984
	s_waitcnt vmcnt(0)
	s_waitcnt lgkmcnt(0)
	s_barrier
	s_mov_b64 s[44:45], exec
	v_readlane_b32 s2, v253, 6
	v_readlane_b32 s3, v253, 7
	s_and_b64 s[2:3], s[44:45], s[2:3]
	s_mov_b64 exec, s[2:3]
	s_cbranch_execz .LBB0_983
	v_readlane_b32 s98, v253, 2
	v_readlane_b32 s99, v253, 3
	v_mov_b32_e32 v1, 0x12000
	s_waitcnt vmcnt(0) expcnt(0) lgkmcnt(0)
	s_load_dwordx2 s[98:99], s[98:99], 0xf8
	ds_read_b128 v[4:7], v1
	s_getreg_b32 s100, hwreg(HW_REG_XCC_ID, 0, 4)
	s_and_b32 s100, s100, 15
	s_lshl_b32 s100, s100, 8
	s_add_u32 s100, s100, 0x38e00000
	s_waitcnt lgkmcnt(0)
	s_add_u32 s100, s98, s100
	s_addc_u32 s101, s99, 0
	v_mov_b32_e32 v2, 1
	v_mov_b32_e32 v3, 0x1400
	global_atomic_add v8, v3, v2, s[100:101] sc0
	v_cvt_f32_u32_e32 v12, v4
	v_rcp_iflag_f32_e32 v12, v12
	v_sub_u32_e32 v13, 0, v4
	s_nop 1
	v_mul_f32_e32 v12, 0x4f7ffffe, v12
	v_cvt_u32_f32_e32 v12, v12
	v_mul_lo_u32 v13, v13, v12
	v_mul_hi_u32 v13, v12, v13
	v_add_u32_e32 v12, v12, v13
	s_waitcnt vmcnt(0)
	buffer_inv sc1
	v_mul_hi_u32 v12, v8, v12
	v_mul_lo_u32 v13, v12, v4
	v_sub_u32_e32 v14, v8, v13
	v_add_u32_e32 v15, 1, v12
	v_cmp_ge_u32_e32 vcc, v14, v4
	v_sub_u32_e32 v13, v14, v4
	s_nop 1
	v_cndmask_b32_e32 v12, v12, v15, vcc
	v_cndmask_b32_e32 v14, v14, v13, vcc
	v_add_u32_e32 v15, 1, v12
	v_cmp_ge_u32_e32 vcc, v14, v4
	s_nop 1
	v_cndmask_b32_e32 v6, v12, v15, vcc
	v_add_u32_e32 v9, 1, v6
	v_mul_lo_u32 v10, v9, v4
	v_mul_lo_u32 v11, v6, v5
	v_add_u32_e32 v8, 1, v8
	v_cmp_ne_u32_e32 vcc, v8, v10
	s_cbranch_vccnz .Lxb_spin_9
	v_mov_b32_e32 v3, 0x1480
	v_add_u32_e32 v14, -1, v4
	v_mul_lo_u32 v14, v14, v6
	buffer_wbl2 sc1
	v_mov_b32_e32 v16, 0

.LBB0_1007:
	s_add_i32 s92, s31, 3
	s_cmp_ge_i32 s92, s71
	s_cbranch_scc1 .LBB0_1070
	s_cmp_lg_u32 s30, s70
	s_mov_b64 s[42:43], -1
	s_cbranch_scc0 .LBB0_1058
	s_waitcnt vmcnt(0)
	s_waitcnt lgkmcnt(0)
	s_barrier
	s_mov_b64 s[42:43], exec
	v_readlane_b32 s2, v253, 6
	v_readlane_b32 s3, v253, 7
	s_and_b64 s[2:3], s[42:43], s[2:3]
	s_mov_b64 exec, s[2:3]
	s_cbranch_execz .LBB0_1057
	v_readlane_b32 s98, v253, 2
	v_readlane_b32 s99, v253, 3
	v_mov_b32_e32 v1, 0x12000
	s_waitcnt vmcnt(0) expcnt(0) lgkmcnt(0)
	s_load_dwordx2 s[98:99], s[98:99], 0xf8
	ds_read_b128 v[4:7], v1
	s_getreg_b32 s100, hwreg(HW_REG_XCC_ID, 0, 4)
	s_and_b32 s100, s100, 15
	s_lshl_b32 s100, s100, 8
	s_add_u32 s100, s100, 0x38e00000
	s_waitcnt lgkmcnt(0)
	s_add_u32 s100, s98, s100
	s_addc_u32 s101, s99, 0
	v_mov_b32_e32 v2, 1
	v_mov_b32_e32 v3, 0x1400
	global_atomic_add v8, v3, v2, s[100:101] sc0
	v_cvt_f32_u32_e32 v12, v4
	v_rcp_iflag_f32_e32 v12, v12
	v_sub_u32_e32 v13, 0, v4
	s_nop 1
	v_mul_f32_e32 v12, 0x4f7ffffe, v12
	v_cvt_u32_f32_e32 v12, v12
	v_mul_lo_u32 v13, v13, v12
	v_mul_hi_u32 v13, v12, v13
	v_add_u32_e32 v12, v12, v13
	s_waitcnt vmcnt(0)
	buffer_inv sc1
	v_mul_hi_u32 v12, v8, v12
	v_mul_lo_u32 v13, v12, v4
	v_sub_u32_e32 v14, v8, v13
	v_add_u32_e32 v15, 1, v12
	v_cmp_ge_u32_e32 vcc, v14, v4
	v_sub_u32_e32 v13, v14, v4
	s_nop 1
	v_cndmask_b32_e32 v12, v12, v15, vcc
	v_cndmask_b32_e32 v14, v14, v13, vcc
	v_add_u32_e32 v15, 1, v12
	v_cmp_ge_u32_e32 vcc, v14, v4
	s_nop 1
	v_cndmask_b32_e32 v6, v12, v15, vcc
	v_add_u32_e32 v9, 1, v6
	v_mul_lo_u32 v10, v9, v4
	v_mul_lo_u32 v11, v6, v5
	v_add_u32_e32 v8, 1, v8
	v_cmp_ne_u32_e32 vcc, v8, v10
	s_cbranch_vccnz .Lxb_spin_10
	v_mov_b32_e32 v3, 0x1480
	v_add_u32_e32 v14, -1, v4
	v_mul_lo_u32 v14, v14, v6
	buffer_wbl2 sc1
	v_mov_b32_e32 v16, 0

.LBB0_1148:
	s_or_b64 exec, exec, s[46:47]
	s_add_i32 s30, s31, 4
	s_cmp_ge_i32 s30, s71
	s_cbranch_scc1 .LBB0_229
	s_cmp_lg_u32 s92, s70
	s_mov_b64 s[42:43], -1
	s_cbranch_scc0 .LBB0_1199
	s_waitcnt vmcnt(0)
	s_barrier
	s_mov_b64 s[42:43], exec
	v_readlane_b32 s2, v253, 6
	v_readlane_b32 s3, v253, 7
	s_and_b64 s[2:3], s[42:43], s[2:3]
	s_mov_b64 exec, s[2:3]
	s_cbranch_execz .LBB0_1198
	v_readlane_b32 s98, v253, 2
	v_readlane_b32 s99, v253, 3
	v_mov_b32_e32 v1, 0x12000
	s_waitcnt vmcnt(0) expcnt(0) lgkmcnt(0)
	s_load_dwordx2 s[98:99], s[98:99], 0xf8
	ds_read_b128 v[4:7], v1
	s_getreg_b32 s100, hwreg(HW_REG_XCC_ID, 0, 4)
	s_and_b32 s100, s100, 15
	s_lshl_b32 s100, s100, 8
	s_add_u32 s100, s100, 0x38e00000
	s_waitcnt lgkmcnt(0)
	s_add_u32 s100, s98, s100
	s_addc_u32 s101, s99, 0
	v_mov_b32_e32 v2, 1
	v_mov_b32_e32 v3, 0x1400
	global_atomic_add v8, v3, v2, s[100:101] sc0
	v_cvt_f32_u32_e32 v12, v4
	v_rcp_iflag_f32_e32 v12, v12
	v_sub_u32_e32 v13, 0, v4
	s_nop 1
	v_mul_f32_e32 v12, 0x4f7ffffe, v12
	v_cvt_u32_f32_e32 v12, v12
	v_mul_lo_u32 v13, v13, v12
	v_mul_hi_u32 v13, v12, v13
	v_add_u32_e32 v12, v12, v13
	s_waitcnt vmcnt(0)
	buffer_inv sc1
	v_mul_hi_u32 v12, v8, v12
	v_mul_lo_u32 v13, v12, v4
	v_sub_u32_e32 v14, v8, v13
	v_add_u32_e32 v15, 1, v12
	v_cmp_ge_u32_e32 vcc, v14, v4
	v_sub_u32_e32 v13, v14, v4
	s_nop 1
	v_cndmask_b32_e32 v12, v12, v15, vcc
	v_cndmask_b32_e32 v14, v14, v13, vcc
	v_add_u32_e32 v15, 1, v12
	v_cmp_ge_u32_e32 vcc, v14, v4
	s_nop 1
	v_cndmask_b32_e32 v6, v12, v15, vcc
	v_add_u32_e32 v9, 1, v6
	v_mul_lo_u32 v10, v9, v4
	v_mul_lo_u32 v11, v6, v5
	v_add_u32_e32 v8, 1, v8
	v_cmp_ne_u32_e32 vcc, v8, v10
	s_cbranch_vccnz .Lxb_spin_11
	v_mov_b32_e32 v3, 0x1480
	v_add_u32_e32 v14, -1, v4
	v_mul_lo_u32 v14, v14, v6
	buffer_wbl2 sc1
	v_mov_b32_e32 v16, 0
